# prompt attention: rows the tasks read later are prefetched to L2 during staging (no wait on them)
# speedup vs baseline: 1.0081x; 1.0081x over previous
; #define LAS __attribute__((address_space(3)))
; __device__ __forceinline__ void attn_prompt_item(const Args& A, LAS unsigned char* lds, int tid, int lane, int wave, int b, int nb, int kvh) {
;     ...
;     for (int idx = tid; idx < 2048; idx += 512) {
;         const int key = idx & 255, ch = idx >> 8; const int pos = (nb - 1) * 128 + key;
;         float kf[8], vf[8];
;         if (pos >= 0) {
;             const size_t row = (size_t)b * SEQ + pos; const bf16_t* kp = Z + row * NZ + O_K + kvh * 64;
;             unpack8(*(const u32x4*)(kp + ch * 8), kf); unpack8(*(const u32x4*)(Z + row * NZ + O_V + kvh * 64 + ch * 8), vf);
;             if (ch < 2) { float pf[8]; unpack8(*(const u32x4*)(kp + (ch ^ 1) * 8), pf);
; #pragma unroll
;                 for (int i = 0; i < 8; ++i) { const float c = ct[pos * 8 + i], s = st[pos * 8 + i]; kf[i] = ch == 0 ? kf[i] * c - pf[i] * s : kf[i] * c + pf[i] * s; } }
;             if (nb == NB - 1 && key >= 128) {
;                 float* ko = A.out + OUT_KP + ((size_t)(b * 128 + key - 128) * 2 + kvh) * 64 + ch * 8; float* vo = A.out + OUT_VP + ((size_t)(b * 128 + key - 128) * 2 + kvh) * 64 + ch * 8;
;                 *(f32x4*)ko = (f32x4){kf[0], kf[1], kf[2], kf[3]}; *(f32x4*)(ko + 4) = (f32x4){kf[4], kf[5], kf[6], kf[7]};
;                 *(f32x4*)vo = (f32x4){vf[0], vf[1], vf[2], vf[3]}; *(f32x4*)(vo + 4) = (f32x4){vf[4], vf[5], vf[6], vf[7]};
;             }
;         } else {
; #pragma unroll
;             for (int i = 0; i < 8; ++i) { kf[i] = 0.f; vf[i] = 0.f; }
;         }
;         *(LAS u32x4*)(lds + AT_K + key * 144 + ch * 16) = pack8(kf);
; #pragma unroll
;         for (int i = 0; i < 8; ++i) *(LAS unsigned short*)(lds + AT_V + (ch * 8 + i) * 528 + key * 2) = (unsigned short)f2bf(vf[i]);
;     ...
;                 const int tq = tt * 32 + mt * 16 + fr; const int pos = nb * 128 + tq; const size_t row = (size_t)b * SEQ + pos;
;                 const bf16_t* qp = Z + row * NZ + O_Q + hq * 64; const int d0 = ks * 32 + q4 * 8;
;                 float qf[8]; unpack8(*(const u32x4*)(qp + d0), qf);
;                 if (ks == 0 && q4 < 2) { float pf[8]; unpack8(*(const u32x4*)(qp + (d0 ^ 8)), pf);
; #pragma unroll
;                     for (int i = 0; i < 8; ++i) { const float c = ct[pos * 8 + i], s = st[pos * 8 + i]; qf[i] = q4 == 0 ? qf[i] * c - pf[i] * s : qf[i] * c + pf[i] * s; } }
.Lpst_ld23:
	global_load_dwordx4 v[94:97], v58, s[16:17]
	global_load_dwordx4 v[98:101], v58, s[16:17] offset:256
	s_mov_b64 exec, s[34:35]
	global_load_dwordx4 v[102:105], v62, s[16:17]
	global_load_dwordx4 v[106:109], v122, s[24:25]
	global_load_dwordx4 v[110:113], v122, s[24:25] offset:16
	global_load_dwordx4 v[114:117], v122, s[28:29]
	global_load_dwordx4 v[118:121], v122, s[28:29] offset:16
	s_mov_b64 exec, -1
	global_load_dwordx4 v[148:151], v59, s[16:17]
	global_load_dwordx4 v[152:155], v59, s[16:17] offset:256
	s_mov_b64 exec, s[34:35]
	global_load_dwordx4 v[156:159], v63, s[16:17]
	global_load_dwordx4 v[160:163], v122, s[24:25] offset:2048
	global_load_dwordx4 v[164:167], v122, s[24:25] offset:2064
	global_load_dwordx4 v[168:171], v122, s[28:29] offset:2048
	global_load_dwordx4 v[172:175], v122, s[28:29] offset:2064
	s_mov_b64 exec, -1
	s_add_i32 s23, s10, s22
	s_mul_i32 s98, s23, 0x1c00
	s_mul_hi_u32 s99, s23, 0x1c00
	s_add_u32 s98, s98, s94
	s_addc_u32 s99, s99, s95
	s_lshl_b32 s59, s21, 9
	s_add_i32 s59, s59, 0x1100
	s_add_u32 s98, s98, s59
	s_addc_u32 s99, s99, 0
	s_lshl_b32 s59, s22, 5
	s_add_u32 s100, s88, s59
	s_addc_u32 s101, s89, 0
	v_bfe_u32 v201, v144, 6, 2
	v_lshlrev_b32_e32 v201, 5, v201
	v_and_b32_e32 v202, 31, v144
	v_add_u32_e32 v202, v202, v201
	v_mul_u32_u24_e32 v202, 0x1c00, v202
	v_lshrrev_b32_e32 v203, 8, v144
	v_bfe_u32 v200, v144, 5, 1
	v_lshl_add_u32 v203, v200, 1, v203
	v_lshl_add_u32 v202, v203, 7, v202
	v_and_b32_e32 v203, 7, v144
	v_lshlrev_b32_e32 v203, 7, v203
	v_lshl_add_u32 v203, v201, 5, v203
	v_bfe_u32 v201, v144, 3, 1
	v_mul_u32_u24_e32 v201, 0x10100, v201
	v_add_u32_e32 v203, v203, v201
	s_nop 4
	global_load_dword v254, v202, s[98:99]
	global_load_dword v254, v202, s[98:99] offset:1536
	s_mov_b64 exec, 0xffff
	global_load_dword v254, v203, s[100:101]
	s_mov_b64 exec, -1
	s_cmp_eq_u32 s20, 0
	s_cbranch_scc1 .Lpst_zero
	s_waitcnt vmcnt(24)
	v_lshlrev_b32_e32 v176, 16, v0
	v_and_b32_e32 v177, 0xffff0000, v0
	v_lshlrev_b32_e32 v178, 16, v1
	v_and_b32_e32 v179, 0xffff0000, v1
	v_lshlrev_b32_e32 v180, 16, v2
	v_and_b32_e32 v181, 0xffff0000, v2
	v_lshlrev_b32_e32 v182, 16, v3
	v_and_b32_e32 v183, 0xffff0000, v3
	s_mov_b64 exec, s[34:35]
	v_lshlrev_b32_e32 v192, 16, v8
	v_mul_f32_e32 v192, v20, v192
	v_xor_b32_e32 v192, v126, v192
	v_fma_f32 v176, v12, v176, v192
	v_and_b32_e32 v192, 0xffff0000, v8
	v_mul_f32_e32 v192, v21, v192
	v_xor_b32_e32 v192, v126, v192
	v_fma_f32 v177, v13, v177, v192
	v_lshlrev_b32_e32 v192, 16, v9
	v_mul_f32_e32 v192, v22, v192
	v_xor_b32_e32 v192, v126, v192
	v_fma_f32 v178, v14, v178, v192
	v_and_b32_e32 v192, 0xffff0000, v9
	v_mul_f32_e32 v192, v23, v192
	v_xor_b32_e32 v192, v126, v192
	v_fma_f32 v179, v15, v179, v192
	v_lshlrev_b32_e32 v192, 16, v10
	v_mul_f32_e32 v192, v24, v192
	v_xor_b32_e32 v192, v126, v192
	v_fma_f32 v180, v16, v180, v192
	v_and_b32_e32 v192, 0xffff0000, v10
	v_mul_f32_e32 v192, v25, v192
	v_xor_b32_e32 v192, v126, v192
	v_fma_f32 v181, v17, v181, v192
	v_lshlrev_b32_e32 v192, 16, v11
	v_mul_f32_e32 v192, v26, v192
	v_xor_b32_e32 v192, v126, v192
	v_fma_f32 v182, v18, v182, v192
	v_and_b32_e32 v192, 0xffff0000, v11
	v_mul_f32_e32 v192, v27, v192
	v_xor_b32_e32 v192, v126, v192
	v_fma_f32 v183, v19, v183, v192
	s_mov_b64 exec, -1
	v_cvt_pk_bf16_f32 v0, v176, v177
	v_cvt_pk_bf16_f32 v1, v178, v179
	v_cvt_pk_bf16_f32 v2, v180, v181
	v_cvt_pk_bf16_f32 v3, v182, v183
	ds_write_b128 v123, v[0:3]
	ds_write_b16 v124, v4 offset:36864
	ds_write_b16_d16_hi v124, v4 offset:37392
	ds_write_b16 v124, v5 offset:37920
	ds_write_b16_d16_hi v124, v5 offset:38448
	ds_write_b16 v124, v6 offset:38976
	ds_write_b16_d16_hi v124, v6 offset:39504
	ds_write_b16 v124, v7 offset:40032
	ds_write_b16_d16_hi v124, v7 offset:40560
	s_waitcnt vmcnt(17)
	v_lshlrev_b32_e32 v176, 16, v28
	v_and_b32_e32 v177, 0xffff0000, v28
	v_lshlrev_b32_e32 v178, 16, v29
	v_and_b32_e32 v179, 0xffff0000, v29
	v_lshlrev_b32_e32 v180, 16, v30
	v_and_b32_e32 v181, 0xffff0000, v30
	v_lshlrev_b32_e32 v182, 16, v31
	v_and_b32_e32 v183, 0xffff0000, v31
	s_mov_b64 exec, s[34:35]
	v_lshlrev_b32_e32 v192, 16, v36
	v_mul_f32_e32 v192, v48, v192
	v_xor_b32_e32 v192, v126, v192
	v_fma_f32 v176, v40, v176, v192
	v_and_b32_e32 v192, 0xffff0000, v36
	v_mul_f32_e32 v192, v49, v192
	v_xor_b32_e32 v192, v126, v192
	v_fma_f32 v177, v41, v177, v192
	v_lshlrev_b32_e32 v192, 16, v37
	v_mul_f32_e32 v192, v50, v192
	v_xor_b32_e32 v192, v126, v192
	v_fma_f32 v178, v42, v178, v192
	v_and_b32_e32 v192, 0xffff0000, v37
	v_mul_f32_e32 v192, v51, v192
	v_xor_b32_e32 v192, v126, v192
	v_fma_f32 v179, v43, v179, v192
	v_lshlrev_b32_e32 v192, 16, v38
	v_mul_f32_e32 v192, v52, v192
	v_xor_b32_e32 v192, v126, v192
	v_fma_f32 v180, v44, v180, v192
	v_and_b32_e32 v192, 0xffff0000, v38
	v_mul_f32_e32 v192, v53, v192
	v_xor_b32_e32 v192, v126, v192
	v_fma_f32 v181, v45, v181, v192
	v_lshlrev_b32_e32 v192, 16, v39
	v_mul_f32_e32 v192, v54, v192
	v_xor_b32_e32 v192, v126, v192
	v_fma_f32 v182, v46, v182, v192
	v_and_b32_e32 v192, 0xffff0000, v39
	v_mul_f32_e32 v192, v55, v192
	v_xor_b32_e32 v192, v126, v192
	v_fma_f32 v183, v47, v183, v192
	s_mov_b64 exec, -1
	v_cvt_pk_bf16_f32 v28, v176, v177
	v_cvt_pk_bf16_f32 v29, v178, v179
	v_cvt_pk_bf16_f32 v30, v180, v181
	v_cvt_pk_bf16_f32 v31, v182, v183
	ds_write_b128 v123, v[28:31] offset:9216
	ds_write_b16 v124, v32 offset:36992
	ds_write_b16_d16_hi v124, v32 offset:37520
	ds_write_b16 v124, v33 offset:38048
	ds_write_b16_d16_hi v124, v33 offset:38576
	ds_write_b16 v124, v34 offset:39104
	ds_write_b16_d16_hi v124, v34 offset:39632
	ds_write_b16 v124, v35 offset:40160
	ds_write_b16_d16_hi v124, v35 offset:40688
	s_branch .Lpst_p23

; #define LAS __attribute__((address_space(3)))
; __device__ __forceinline__ unsigned f2bf(float f) { return pk2(f, 0.f) & 0xffffu; }
; __device__ __forceinline__ void unpack8(u32x4 u, float* f) { f[0] = bflo(u.x); f[1] = bfhi(u.x); f[2] = bflo(u.y); f[3] = bfhi(u.y); f[4] = bflo(u.z); f[5] = bfhi(u.z); f[6] = bflo(u.w); f[7] = bfhi(u.w); }
; __device__ __forceinline__ u32x4 pack8(const float* f) { u32x4 o; o.x = pk2(f[0], f[1]); o.y = pk2(f[2], f[3]); o.z = pk2(f[4], f[5]); o.w = pk2(f[6], f[7]); return o; }
; __device__ __forceinline__ void attn_prompt_item(const Args& A, LAS unsigned char* lds, int tid, int lane, int wave, int b, int nb, int kvh) {
;     ...
;         if (pos >= 0) {
;             const size_t row = (size_t)b * SEQ + pos; const bf16_t* kp = Z + row * NZ + O_K + kvh * 64;
;             unpack8(*(const u32x4*)(kp + ch * 8), kf); unpack8(*(const u32x4*)(Z + row * NZ + O_V + kvh * 64 + ch * 8), vf);
;             if (ch < 2) { float pf[8]; unpack8(*(const u32x4*)(kp + (ch ^ 1) * 8), pf);
; #pragma unroll
;                 for (int i = 0; i < 8; ++i) { const float c = ct[pos * 8 + i], s = st[pos * 8 + i]; kf[i] = ch == 0 ? kf[i] * c - pf[i] * s : kf[i] * c + pf[i] * s; } }
;             if (nb == NB - 1 && key >= 128) {
;                 float* ko = A.out + OUT_KP + ((size_t)(b * 128 + key - 128) * 2 + kvh) * 64 + ch * 8; float* vo = A.out + OUT_VP + ((size_t)(b * 128 + key - 128) * 2 + kvh) * 64 + ch * 8;
;                 *(f32x4*)ko = (f32x4){kf[0], kf[1], kf[2], kf[3]}; *(f32x4*)(ko + 4) = (f32x4){kf[4], kf[5], kf[6], kf[7]};
;                 *(f32x4*)vo = (f32x4){vf[0], vf[1], vf[2], vf[3]}; *(f32x4*)(vo + 4) = (f32x4){vf[4], vf[5], vf[6], vf[7]};
;             }
;         } else {
; #pragma unroll
;             for (int i = 0; i < 8; ++i) { kf[i] = 0.f; vf[i] = 0.f; }
;         }
;         *(LAS u32x4*)(lds + AT_K + key * 144 + ch * 16) = pack8(kf);
; #pragma unroll
;         for (int i = 0; i < 8; ++i) *(LAS unsigned short*)(lds + AT_V + (ch * 8 + i) * 528 + key * 2) = (unsigned short)f2bf(vf[i]);
.Lpst_p23:
	s_waitcnt vmcnt(10)
	v_lshlrev_b32_e32 v176, 16, v94
	v_and_b32_e32 v177, 0xffff0000, v94
	v_lshlrev_b32_e32 v178, 16, v95
	v_and_b32_e32 v179, 0xffff0000, v95
	v_lshlrev_b32_e32 v180, 16, v96
	v_and_b32_e32 v181, 0xffff0000, v96
	v_lshlrev_b32_e32 v182, 16, v97
	v_and_b32_e32 v183, 0xffff0000, v97
	s_mov_b64 exec, s[34:35]
	v_lshlrev_b32_e32 v192, 16, v102
	v_mul_f32_e32 v192, v114, v192
	v_xor_b32_e32 v192, v126, v192
	v_fma_f32 v176, v106, v176, v192
	v_and_b32_e32 v192, 0xffff0000, v102
	v_mul_f32_e32 v192, v115, v192
	v_xor_b32_e32 v192, v126, v192
	v_fma_f32 v177, v107, v177, v192
	v_lshlrev_b32_e32 v192, 16, v103
	v_mul_f32_e32 v192, v116, v192
	v_xor_b32_e32 v192, v126, v192
	v_fma_f32 v178, v108, v178, v192
	v_and_b32_e32 v192, 0xffff0000, v103
	v_mul_f32_e32 v192, v117, v192
	v_xor_b32_e32 v192, v126, v192
	v_fma_f32 v179, v109, v179, v192
	v_lshlrev_b32_e32 v192, 16, v104
	v_mul_f32_e32 v192, v118, v192
	v_xor_b32_e32 v192, v126, v192
	v_fma_f32 v180, v110, v180, v192
	v_and_b32_e32 v192, 0xffff0000, v104
	v_mul_f32_e32 v192, v119, v192
	v_xor_b32_e32 v192, v126, v192
	v_fma_f32 v181, v111, v181, v192
	v_lshlrev_b32_e32 v192, 16, v105
	v_mul_f32_e32 v192, v120, v192
	v_xor_b32_e32 v192, v126, v192
	v_fma_f32 v182, v112, v182, v192
	v_and_b32_e32 v192, 0xffff0000, v105
	v_mul_f32_e32 v192, v121, v192
	v_xor_b32_e32 v192, v126, v192
	v_fma_f32 v183, v113, v183, v192
	s_mov_b64 exec, -1
	v_cvt_pk_bf16_f32 v94, v176, v177
	v_cvt_pk_bf16_f32 v95, v178, v179
	v_cvt_pk_bf16_f32 v96, v180, v181
	v_cvt_pk_bf16_f32 v97, v182, v183
	ds_write_b128 v123, v[94:97] offset:18432
	ds_write_b16 v124, v98 offset:37120
	ds_write_b16_d16_hi v124, v98 offset:37648
	ds_write_b16 v124, v99 offset:38176
	ds_write_b16_d16_hi v124, v99 offset:38704
	ds_write_b16 v124, v100 offset:39232
	ds_write_b16_d16_hi v124, v100 offset:39760
	ds_write_b16 v124, v101 offset:40288
	ds_write_b16_d16_hi v124, v101 offset:40816
	s_cmp_eq_u32 s20, 15
	s_cbranch_scc0 .Lpst_noout2
	v_lshlrev_b32_e32 v184, 16, v98
	v_and_b32_e32 v185, 0xffff0000, v98
	v_lshlrev_b32_e32 v186, 16, v99
	v_and_b32_e32 v187, 0xffff0000, v99
	v_lshlrev_b32_e32 v188, 16, v100
	v_and_b32_e32 v189, 0xffff0000, v100
	v_lshlrev_b32_e32 v190, 16, v101
	v_and_b32_e32 v191, 0xffff0000, v101
	global_store_dwordx4 v125, v[176:179], s[12:13]
	global_store_dwordx4 v125, v[180:183], s[12:13] offset:16
	global_store_dwordx4 v125, v[184:187], s[64:65]
	global_store_dwordx4 v125, v[188:191], s[64:65] offset:16
.Lpst_noout2:
	s_waitcnt vmcnt(3)
	v_lshlrev_b32_e32 v176, 16, v148
	v_and_b32_e32 v177, 0xffff0000, v148
	v_lshlrev_b32_e32 v178, 16, v149
	v_and_b32_e32 v179, 0xffff0000, v149
	v_lshlrev_b32_e32 v180, 16, v150
	v_and_b32_e32 v181, 0xffff0000, v150
	v_lshlrev_b32_e32 v182, 16, v151
	v_and_b32_e32 v183, 0xffff0000, v151
	s_mov_b64 exec, s[34:35]
	v_lshlrev_b32_e32 v192, 16, v156
	v_mul_f32_e32 v192, v168, v192
	v_xor_b32_e32 v192, v126, v192
	v_fma_f32 v176, v160, v176, v192
	v_and_b32_e32 v192, 0xffff0000, v156
	v_mul_f32_e32 v192, v169, v192
	v_xor_b32_e32 v192, v126, v192
	v_fma_f32 v177, v161, v177, v192
	v_lshlrev_b32_e32 v192, 16, v157
	v_mul_f32_e32 v192, v170, v192
	v_xor_b32_e32 v192, v126, v192
	v_fma_f32 v178, v162, v178, v192
	v_and_b32_e32 v192, 0xffff0000, v157
	v_mul_f32_e32 v192, v171, v192
	v_xor_b32_e32 v192, v126, v192
	v_fma_f32 v179, v163, v179, v192
	v_lshlrev_b32_e32 v192, 16, v158
	v_mul_f32_e32 v192, v172, v192
	v_xor_b32_e32 v192, v126, v192
	v_fma_f32 v180, v164, v180, v192
	v_and_b32_e32 v192, 0xffff0000, v158
	v_mul_f32_e32 v192, v173, v192
	v_xor_b32_e32 v192, v126, v192
	v_fma_f32 v181, v165, v181, v192
	v_lshlrev_b32_e32 v192, 16, v159
	v_mul_f32_e32 v192, v174, v192
	v_xor_b32_e32 v192, v126, v192
	v_fma_f32 v182, v166, v182, v192
	v_and_b32_e32 v192, 0xffff0000, v159
	v_mul_f32_e32 v192, v175, v192
	v_xor_b32_e32 v192, v126, v192
	v_fma_f32 v183, v167, v183, v192
	s_mov_b64 exec, -1
	v_cvt_pk_bf16_f32 v148, v176, v177
	v_cvt_pk_bf16_f32 v149, v178, v179
	v_cvt_pk_bf16_f32 v150, v180, v181
	v_cvt_pk_bf16_f32 v151, v182, v183
	ds_write_b128 v123, v[148:151] offset:27648
	ds_write_b16 v124, v152 offset:37248
	ds_write_b16_d16_hi v124, v152 offset:37776
	ds_write_b16 v124, v153 offset:38304
	ds_write_b16_d16_hi v124, v153 offset:38832
	ds_write_b16 v124, v154 offset:39360
	ds_write_b16_d16_hi v124, v154 offset:39888
	ds_write_b16 v124, v155 offset:40416
	ds_write_b16_d16_hi v124, v155 offset:40944
	s_cmp_eq_u32 s20, 15
	s_cbranch_scc0 .Lpst_noout3
	v_lshlrev_b32_e32 v184, 16, v152
	v_and_b32_e32 v185, 0xffff0000, v152
	v_lshlrev_b32_e32 v186, 16, v153
	v_and_b32_e32 v187, 0xffff0000, v153
	v_lshlrev_b32_e32 v188, 16, v154
	v_and_b32_e32 v189, 0xffff0000, v154
	v_lshlrev_b32_e32 v190, 16, v155
	v_and_b32_e32 v191, 0xffff0000, v155
	global_store_dwordx4 v193, v[176:179], s[12:13]
	global_store_dwordx4 v193, v[180:183], s[12:13] offset:16
	global_store_dwordx4 v193, v[184:187], s[64:65]
	global_store_dwordx4 v193, v[188:191], s[64:65] offset:16
